# NA latent-item epilogue: the 7 gate-chunk prefetch loads issued before the item's last softmax/P.V block (2 copies) instead of at the epilogue head
# speedup vs baseline: 1.0038x; 1.0038x over previous
.LBB0_1084:
	v_mov_b32_e32 v151, v149
	v_lshl_add_u64 v[32:33], s[94:95], 0, v[150:151]
	v_lshlrev_b32_e32 v34, 1, v144
	v_mov_b32_e32 v35, v149
	v_lshl_add_u64 v[32:33], v[32:33], 0, v[34:35]
	global_load_dwordx2 v[34:35], v[32:33], off
	v_bfe_u32 v198, v192, 5, 1
	v_lshlrev_b32_e32 v198, 3, v198
	v_mov_b32_e32 v199, 0
	v_lshl_add_u64 v[198:199], v[32:33], 0, v[198:199]
	v_rcp_f32_e32 v36, v127
	s_waitcnt vmcnt(0)
	v_lshlrev_b32_e32 v37, 16, v34
	v_mul_f32_e32 v16, v16, v36
	v_mul_f32_e32 v17, v17, v36
	v_mul_f32_e32 v18, v18, v36
	v_mul_f32_e32 v19, v19, v36
	v_and_b32_e32 v34, 0xffff0000, v34
	v_lshlrev_b32_e32 v38, 16, v35
	v_and_b32_e32 v35, 0xffff0000, v35
	v_mul_f32_e32 v16, v16, v37
	v_mul_f32_e32 v17, v17, v34
	v_mul_f32_e32 v18, v18, v38
	v_mul_f32_e32 v19, v19, v35
	v_cvt_pk_bf16_f32 v16, v16, v17
	v_cvt_pk_bf16_f32 v17, v18, v19
	v_mul_f32_e32 v20, v20, v36
	v_mul_f32_e32 v21, v21, v36
	v_mul_f32_e32 v22, v22, v36
	v_mul_f32_e32 v23, v23, v36
	v_mov_b32_e32 v200, v16
	v_mov_b32_e32 v201, v17
	v_mul_f32_e32 v0, v0, v36
	v_mul_f32_e32 v1, v1, v36
	v_mul_f32_e32 v2, v2, v36
	v_mul_f32_e32 v3, v3, v36
	v_mul_f32_e32 v4, v4, v36
	v_mul_f32_e32 v5, v5, v36
	v_mul_f32_e32 v6, v6, v36
	v_mul_f32_e32 v7, v7, v36
	v_lshlrev_b32_e32 v16, 16, v240
	v_and_b32_e32 v17, 0xffff0000, v240
	v_lshlrev_b32_e32 v18, 16, v241
	v_and_b32_e32 v19, 0xffff0000, v241
	v_mul_f32_e32 v16, v20, v16
	v_mul_f32_e32 v17, v21, v17
	v_mul_f32_e32 v18, v22, v18
	v_mul_f32_e32 v19, v23, v19
	v_cvt_pk_bf16_f32 v16, v16, v17
	v_cvt_pk_bf16_f32 v17, v18, v19
	v_mul_f32_e32 v20, v24, v36
	v_mul_f32_e32 v21, v25, v36
	v_mul_f32_e32 v22, v26, v36
	v_mul_f32_e32 v23, v27, v36
	v_mov_b32_e32 v202, v16
	v_mov_b32_e32 v203, v17
	s_nop 1
	v_permlane32_swap_b32_e32 v200, v202
	v_permlane32_swap_b32_e32 v201, v203
	global_store_dwordx4 v[198:199], v[200:203], off
	v_lshlrev_b32_e32 v16, 16, v242
	v_and_b32_e32 v17, 0xffff0000, v242
	v_lshlrev_b32_e32 v18, 16, v243
	v_and_b32_e32 v19, 0xffff0000, v243
	v_mul_f32_e32 v16, v20, v16
	v_mul_f32_e32 v17, v21, v17
	v_mul_f32_e32 v18, v22, v18
	v_mul_f32_e32 v19, v23, v19
	v_cvt_pk_bf16_f32 v16, v16, v17
	v_cvt_pk_bf16_f32 v17, v18, v19
	v_mul_f32_e32 v20, v28, v36
	v_mul_f32_e32 v21, v29, v36
	v_mul_f32_e32 v22, v30, v36
	v_mul_f32_e32 v23, v31, v36
	v_mov_b32_e32 v200, v16
	v_mov_b32_e32 v201, v17
	v_lshlrev_b32_e32 v16, 16, v244
	v_and_b32_e32 v17, 0xffff0000, v244
	v_lshlrev_b32_e32 v18, 16, v245
	v_and_b32_e32 v19, 0xffff0000, v245
	v_mul_f32_e32 v16, v20, v16
	v_mul_f32_e32 v17, v21, v17
	v_mul_f32_e32 v18, v22, v18
	v_mul_f32_e32 v19, v23, v19
	v_cvt_pk_bf16_f32 v16, v16, v17
	v_cvt_pk_bf16_f32 v17, v18, v19
	s_nop 0
	v_mov_b32_e32 v202, v16
	v_mov_b32_e32 v203, v17
	s_nop 1
	v_permlane32_swap_b32_e32 v200, v202
	v_permlane32_swap_b32_e32 v201, v203
	global_store_dwordx4 v[198:199], v[200:203], off offset:32
	v_lshlrev_b32_e32 v16, 16, v246
	v_and_b32_e32 v17, 0xffff0000, v246
	v_lshlrev_b32_e32 v18, 16, v247
	v_and_b32_e32 v19, 0xffff0000, v247
	v_mul_f32_e32 v0, v0, v16
	v_mul_f32_e32 v1, v1, v17
	v_mul_f32_e32 v2, v2, v18
	v_mul_f32_e32 v3, v3, v19
	v_cvt_pk_bf16_f32 v0, v0, v1
	v_cvt_pk_bf16_f32 v1, v2, v3
	s_nop 0
	v_mov_b32_e32 v200, v0
	v_mov_b32_e32 v201, v1
	v_lshlrev_b32_e32 v0, 16, v248
	v_and_b32_e32 v1, 0xffff0000, v248
	v_lshlrev_b32_e32 v2, 16, v249
	v_and_b32_e32 v3, 0xffff0000, v249
	v_mul_f32_e32 v0, v4, v0
	v_mul_f32_e32 v1, v5, v1
	v_mul_f32_e32 v2, v6, v2
	v_mul_f32_e32 v3, v7, v3
	v_cvt_pk_bf16_f32 v0, v0, v1
	v_cvt_pk_bf16_f32 v1, v2, v3
	v_mul_f32_e32 v4, v8, v36
	v_mul_f32_e32 v5, v9, v36
	v_mul_f32_e32 v6, v10, v36
	v_mul_f32_e32 v7, v11, v36
	v_mov_b32_e32 v202, v0
	v_mov_b32_e32 v203, v1
	s_nop 1
	v_permlane32_swap_b32_e32 v200, v202
	v_permlane32_swap_b32_e32 v201, v203
	global_store_dwordx4 v[198:199], v[200:203], off offset:64
	v_lshlrev_b32_e32 v0, 16, v250
	v_and_b32_e32 v1, 0xffff0000, v250
	v_lshlrev_b32_e32 v2, 16, v251
	v_and_b32_e32 v3, 0xffff0000, v251
	v_mul_f32_e32 v0, v4, v0
	v_mul_f32_e32 v1, v5, v1
	v_mul_f32_e32 v2, v6, v2
	v_mul_f32_e32 v3, v7, v3
	v_cvt_pk_bf16_f32 v0, v0, v1
	v_cvt_pk_bf16_f32 v1, v2, v3
	v_mul_f32_e32 v4, v12, v36
	v_mul_f32_e32 v5, v13, v36
	v_mov_b32_e32 v200, v0
	v_mov_b32_e32 v201, v1
	v_mul_f32_e32 v6, v14, v36
	v_mul_f32_e32 v7, v15, v36
	v_lshlrev_b32_e32 v0, 16, v252
	v_and_b32_e32 v1, 0xffff0000, v252
	v_lshlrev_b32_e32 v2, 16, v253
	v_and_b32_e32 v3, 0xffff0000, v253
	v_mul_f32_e32 v0, v4, v0
	v_mul_f32_e32 v1, v5, v1
	v_mul_f32_e32 v2, v6, v2
	v_mul_f32_e32 v3, v7, v3
	v_cvt_pk_bf16_f32 v0, v0, v1
	v_cvt_pk_bf16_f32 v1, v2, v3
	v_mov_b32_e32 v202, v0
	v_mov_b32_e32 v203, v1
	s_nop 1
	v_permlane32_swap_b32_e32 v200, v202
	v_permlane32_swap_b32_e32 v201, v203
	global_store_dwordx4 v[198:199], v[200:203], off offset:96
	s_barrier

.LBB0_1317:
	v_mov_b32_e32 v204, v150
	v_mov_b32_e32 v205, v149
	v_lshl_add_u64 v[206:207], s[94:95], 0, v[204:205]
	v_lshlrev_b32_e32 v204, 1, v144
	v_lshl_add_u64 v[206:207], v[206:207], 0, v[204:205]
	global_load_dwordx2 v[240:241], v[206:207], off offset:16
	global_load_dwordx2 v[242:243], v[206:207], off offset:32
	global_load_dwordx2 v[244:245], v[206:207], off offset:48
	global_load_dwordx2 v[246:247], v[206:207], off offset:64
	global_load_dwordx2 v[248:249], v[206:207], off offset:80
	global_load_dwordx2 v[250:251], v[206:207], off offset:96
	global_load_dwordx2 v[252:253], v[206:207], off offset:112
	s_and_b64 vcc, exec, s[70:71]
	s_cbranch_vccnz .LBB0_1319
	v_exp_f32_e32 v36, v48
	v_add_f32_e32 v33, 0, v166
	v_exp_f32_e32 v37, v49
	v_add_f32_e32 v33, v167, v33
	v_exp_f32_e32 v38, v50
	v_add_f32_e32 v33, v168, v33
	v_exp_f32_e32 v39, v51
	v_add_f32_e32 v33, v169, v33
	v_exp_f32_e32 v40, v52
	v_add_f32_e32 v33, v36, v33
	v_exp_f32_e32 v41, v53
	v_add_f32_e32 v33, v37, v33
	v_exp_f32_e32 v42, v54
	v_add_f32_e32 v33, v38, v33
	v_exp_f32_e32 v43, v55
	v_add_f32_e32 v33, v39, v33
	v_exp_f32_e32 v44, v56
	v_add_f32_e32 v33, v40, v33
	v_exp_f32_e32 v45, v57
	v_add_f32_e32 v33, v41, v33
	v_exp_f32_e32 v46, v58
	v_add_f32_e32 v33, v42, v33
	v_exp_f32_e32 v47, v59
	v_add_f32_e32 v33, v43, v33
	v_exp_f32_e32 v48, v60
	v_add_f32_e32 v33, v44, v33
	v_exp_f32_e32 v49, v61
	v_add_f32_e32 v33, v45, v33
	v_exp_f32_e32 v50, v62
	v_add_f32_e32 v33, v46, v33
	v_exp_f32_e32 v51, v63
	v_add_f32_e32 v33, v47, v33
	v_add_f32_e32 v33, v48, v33
	v_add_f32_e32 v33, v49, v33
	v_add_f32_e32 v33, v50, v33
	v_add_f32_e32 v33, v51, v33
	v_mov_b32_e32 v34, v33
	s_nop 1
	v_permlane32_swap_b32_e32 v33, v34
	v_add_f32_e32 v64, v33, v34
	v_fmac_f32_e32 v64, v176, v32
	v_cvt_pk_bf16_f32 v32, v149, v149
	v_cvt_pk_bf16_f32 v33, v149, v149
	v_cvt_pk_bf16_f32 v34, v166, v167
	v_cvt_pk_bf16_f32 v35, v168, v169
	v_cvt_pk_bf16_f32 v36, v36, v37
	v_cvt_pk_bf16_f32 v37, v38, v39
	v_cvt_pk_bf16_f32 v38, v40, v41
	v_cvt_pk_bf16_f32 v39, v42, v43
	v_cvt_pk_bf16_f32 v40, v44, v45
	v_cvt_pk_bf16_f32 v41, v46, v47
	v_cvt_pk_bf16_f32 v42, v48, v49
	v_cvt_pk_bf16_f32 v43, v50, v51
	ds_read_b64_tr_b16 v[44:45], v185 offset:0
	ds_read_b64_tr_b16 v[46:47], v185 offset:0x400
	ds_read_b64_tr_b16 v[48:49], v185 offset:0x800
	ds_read_b64_tr_b16 v[50:51], v185 offset:0xc00
	ds_read_b64_tr_b16 v[52:53], v185 offset:0x1000
	ds_read_b64_tr_b16 v[54:55], v185 offset:0x1400
	ds_read_b64_tr_b16 v[56:57], v185 offset:0x1800
	ds_read_b64_tr_b16 v[58:59], v185 offset:0x1c00
	s_waitcnt lgkmcnt(0)
	s_mov_b32 s77, s76
	s_mov_b32 s78, s76
	s_mov_b32 s79, s76
	v_mov_b64_e32 v[60:61], s[76:77]
	v_mov_b64_e32 v[62:63], s[78:79]
	s_nop 1
	v_mfma_f32_32x32x16_bf16 v[16:31], v[44:47], v[60:63], v[16:31]
	ds_read_b64_tr_b16 v[44:45], v185 offset:0x200
	ds_read_b64_tr_b16 v[46:47], v185 offset:0x600
	v_mfma_f32_32x32x16_bf16 v[16:31], v[48:51], v[32:35], v[16:31]
	ds_read_b64_tr_b16 v[48:49], v185 offset:0xa00
	ds_read_b64_tr_b16 v[50:51], v185 offset:0xe00
	v_mfma_f32_32x32x16_bf16 v[16:31], v[52:55], v[36:39], v[16:31]
	ds_read_b64_tr_b16 v[52:53], v185 offset:0x1200
	ds_read_b64_tr_b16 v[54:55], v185 offset:0x1600
	v_mfma_f32_32x32x16_bf16 v[16:31], v[56:59], v[40:43], v[16:31]
	ds_read_b64_tr_b16 v[56:57], v185 offset:0x1a00
	ds_read_b64_tr_b16 v[58:59], v185 offset:0x1e00
	s_waitcnt lgkmcnt(0)
	v_mfma_f32_32x32x16_bf16 v[0:15], v[44:47], v[60:63], v[0:15]
	v_mov_b32_e32 v176, v64
	v_mfma_f32_32x32x16_bf16 v[0:15], v[48:51], v[32:35], v[0:15]
	v_mfma_f32_32x32x16_bf16 v[0:15], v[52:55], v[36:39], v[0:15]
	v_mfma_f32_32x32x16_bf16 v[0:15], v[56:59], v[40:43], v[0:15]
.LBB0_1319:
	v_mov_b32_e32 v151, v149
	v_lshl_add_u64 v[32:33], s[94:95], 0, v[150:151]
	v_lshlrev_b32_e32 v34, 1, v144
	v_mov_b32_e32 v35, v149
	v_lshl_add_u64 v[32:33], v[32:33], 0, v[34:35]
	global_load_dwordx2 v[34:35], v[32:33], off
	v_bfe_u32 v198, v192, 5, 1
	v_lshlrev_b32_e32 v198, 3, v198
	v_mov_b32_e32 v199, 0
	v_lshl_add_u64 v[198:199], v[32:33], 0, v[198:199]
	v_rcp_f32_e32 v36, v176
	s_mov_b64 s[70:71], 0
	v_mul_f32_e32 v16, v16, v36
	v_mul_f32_e32 v17, v17, v36
	v_mul_f32_e32 v18, v18, v36
	v_mul_f32_e32 v19, v19, v36
	v_mul_f32_e32 v20, v20, v36
	v_mul_f32_e32 v21, v21, v36
	v_mul_f32_e32 v22, v22, v36
	v_mul_f32_e32 v23, v23, v36
	v_mul_f32_e32 v0, v0, v36
	v_mul_f32_e32 v1, v1, v36
	v_mul_f32_e32 v2, v2, v36
	v_mul_f32_e32 v3, v3, v36
	v_mul_f32_e32 v4, v4, v36
	v_mul_f32_e32 v5, v5, v36
	v_mul_f32_e32 v6, v6, v36
	v_mul_f32_e32 v7, v7, v36
	s_waitcnt vmcnt(0)
	v_lshlrev_b32_e32 v37, 16, v34
	v_and_b32_e32 v34, 0xffff0000, v34
	v_lshlrev_b32_e32 v38, 16, v35
	v_and_b32_e32 v35, 0xffff0000, v35
	v_mul_f32_e32 v16, v16, v37
	v_mul_f32_e32 v17, v17, v34
	v_mul_f32_e32 v18, v18, v38
	v_mul_f32_e32 v19, v19, v35
	v_cvt_pk_bf16_f32 v16, v16, v17
	v_cvt_pk_bf16_f32 v17, v18, v19
	s_nop 0
	v_mov_b32_e32 v200, v16
	v_mov_b32_e32 v201, v17
	v_lshlrev_b32_e32 v16, 16, v240
	v_and_b32_e32 v17, 0xffff0000, v240
	v_lshlrev_b32_e32 v18, 16, v241
	v_and_b32_e32 v19, 0xffff0000, v241
	v_mul_f32_e32 v16, v20, v16
	v_mul_f32_e32 v17, v21, v17
	v_mul_f32_e32 v18, v22, v18
	v_mul_f32_e32 v19, v23, v19
	v_cvt_pk_bf16_f32 v16, v16, v17
	v_cvt_pk_bf16_f32 v17, v18, v19
	v_mul_f32_e32 v20, v24, v36
	v_mul_f32_e32 v21, v25, v36
	v_mul_f32_e32 v22, v26, v36
	v_mul_f32_e32 v23, v27, v36
	v_mov_b32_e32 v202, v16
	v_mov_b32_e32 v203, v17
	s_nop 1
	v_permlane32_swap_b32_e32 v200, v202
	v_permlane32_swap_b32_e32 v201, v203
	global_store_dwordx4 v[198:199], v[200:203], off
	v_lshlrev_b32_e32 v16, 16, v242
	v_and_b32_e32 v17, 0xffff0000, v242
	v_lshlrev_b32_e32 v18, 16, v243
	v_and_b32_e32 v19, 0xffff0000, v243
	v_mul_f32_e32 v16, v20, v16
	v_mul_f32_e32 v17, v21, v17
	v_mul_f32_e32 v18, v22, v18
	v_mul_f32_e32 v19, v23, v19
	v_cvt_pk_bf16_f32 v16, v16, v17
	v_cvt_pk_bf16_f32 v17, v18, v19
	v_mul_f32_e32 v20, v28, v36
	v_mul_f32_e32 v21, v29, v36
	v_mul_f32_e32 v22, v30, v36
	v_mul_f32_e32 v23, v31, v36
	v_mov_b32_e32 v200, v16
	v_mov_b32_e32 v201, v17
	v_lshlrev_b32_e32 v16, 16, v244
	v_and_b32_e32 v17, 0xffff0000, v244
	v_lshlrev_b32_e32 v18, 16, v245
	v_and_b32_e32 v19, 0xffff0000, v245
	v_mul_f32_e32 v16, v20, v16
	v_mul_f32_e32 v17, v21, v17
	v_mul_f32_e32 v18, v22, v18
	v_mul_f32_e32 v19, v23, v19
	v_cvt_pk_bf16_f32 v16, v16, v17
	v_cvt_pk_bf16_f32 v17, v18, v19
	s_nop 0
	v_mov_b32_e32 v202, v16
	v_mov_b32_e32 v203, v17
	s_nop 1
	v_permlane32_swap_b32_e32 v200, v202
	v_permlane32_swap_b32_e32 v201, v203
	global_store_dwordx4 v[198:199], v[200:203], off offset:32
	v_lshlrev_b32_e32 v16, 16, v246
	v_and_b32_e32 v17, 0xffff0000, v246
	v_lshlrev_b32_e32 v18, 16, v247
	v_and_b32_e32 v19, 0xffff0000, v247
	v_mul_f32_e32 v0, v0, v16
	v_mul_f32_e32 v1, v1, v17
	v_mul_f32_e32 v2, v2, v18
	v_mul_f32_e32 v3, v3, v19
	v_cvt_pk_bf16_f32 v0, v0, v1
	v_cvt_pk_bf16_f32 v1, v2, v3
	s_nop 0
	v_mov_b32_e32 v200, v0
	v_mov_b32_e32 v201, v1
	v_lshlrev_b32_e32 v0, 16, v248
	v_and_b32_e32 v1, 0xffff0000, v248
	v_lshlrev_b32_e32 v2, 16, v249
	v_and_b32_e32 v3, 0xffff0000, v249
	v_mul_f32_e32 v0, v4, v0
	v_mul_f32_e32 v1, v5, v1
	v_mul_f32_e32 v2, v6, v2
	v_mul_f32_e32 v3, v7, v3
	v_cvt_pk_bf16_f32 v0, v0, v1
	v_cvt_pk_bf16_f32 v1, v2, v3
	v_mul_f32_e32 v4, v8, v36
	v_mul_f32_e32 v5, v9, v36
	v_mul_f32_e32 v6, v10, v36
	v_mul_f32_e32 v7, v11, v36
	v_mov_b32_e32 v202, v0
	v_mov_b32_e32 v203, v1
	s_nop 1
	v_permlane32_swap_b32_e32 v200, v202
	v_permlane32_swap_b32_e32 v201, v203
	global_store_dwordx4 v[198:199], v[200:203], off offset:64
	v_lshlrev_b32_e32 v0, 16, v250
	v_and_b32_e32 v1, 0xffff0000, v250
	v_lshlrev_b32_e32 v2, 16, v251
	v_and_b32_e32 v3, 0xffff0000, v251
	v_mul_f32_e32 v0, v4, v0
	v_mul_f32_e32 v1, v5, v1
	v_mul_f32_e32 v2, v6, v2
	v_mul_f32_e32 v3, v7, v3
	v_cvt_pk_bf16_f32 v0, v0, v1
	v_cvt_pk_bf16_f32 v1, v2, v3
	v_mul_f32_e32 v4, v12, v36
	v_mul_f32_e32 v5, v13, v36
	v_mov_b32_e32 v200, v0
	v_mov_b32_e32 v201, v1
	v_mul_f32_e32 v6, v14, v36
	v_mul_f32_e32 v7, v15, v36
	v_lshlrev_b32_e32 v0, 16, v252
	v_and_b32_e32 v1, 0xffff0000, v252
	v_lshlrev_b32_e32 v2, 16, v253
	v_and_b32_e32 v3, 0xffff0000, v253
	v_mul_f32_e32 v0, v4, v0
	v_mul_f32_e32 v1, v5, v1
	v_mul_f32_e32 v2, v6, v2
	v_mul_f32_e32 v3, v7, v3
	v_cvt_pk_bf16_f32 v0, v0, v1
	v_cvt_pk_bf16_f32 v1, v2, v3
	v_mov_b32_e32 v202, v0
	v_mov_b32_e32 v203, v1
	s_nop 1
	v_permlane32_swap_b32_e32 v200, v202
	v_permlane32_swap_b32_e32 v201, v203
	global_store_dwordx4 v[198:199], v[200:203], off offset:96
	s_barrier

.LBB0_1545:
	v_mov_b32_e32 v204, v150
	v_mov_b32_e32 v205, v149
	v_lshl_add_u64 v[206:207], s[94:95], 0, v[204:205]
	v_lshlrev_b32_e32 v204, 1, v144
	v_lshl_add_u64 v[206:207], v[206:207], 0, v[204:205]
	global_load_dwordx2 v[240:241], v[206:207], off offset:16
	global_load_dwordx2 v[242:243], v[206:207], off offset:32
	global_load_dwordx2 v[244:245], v[206:207], off offset:48
	global_load_dwordx2 v[246:247], v[206:207], off offset:64
	global_load_dwordx2 v[248:249], v[206:207], off offset:80
	global_load_dwordx2 v[250:251], v[206:207], off offset:96
	global_load_dwordx2 v[252:253], v[206:207], off offset:112
	s_and_b64 vcc, exec, s[70:71]
	s_cbranch_vccnz .LBB0_1084
	v_add_f32_e32 v33, 0, v142
	v_add_f32_e32 v33, v143, v33
	v_add_f32_e32 v33, v160, v33
	v_add_f32_e32 v33, v161, v33
	v_add_f32_e32 v33, v164, v33
	v_add_f32_e32 v33, v165, v33
	v_add_f32_e32 v33, v166, v33
	v_add_f32_e32 v33, v167, v33
	v_add_f32_e32 v33, v168, v33
	v_add_f32_e32 v33, v169, v33
	v_add_f32_e32 v33, v170, v33
	v_add_f32_e32 v33, v171, v33
	v_exp_f32_e32 v40, v34
	v_add_f32_e32 v33, v172, v33
	v_exp_f32_e32 v41, v35
	v_add_f32_e32 v33, v173, v33
	v_exp_f32_e32 v42, v162
	v_add_f32_e32 v33, v174, v33
	v_exp_f32_e32 v43, v163
	v_add_f32_e32 v33, v175, v33
	v_add_f32_e32 v33, v40, v33
	v_add_f32_e32 v33, v41, v33
	v_add_f32_e32 v33, v42, v33
	v_add_f32_e32 v33, v43, v33
	v_mov_b32_e32 v34, v33
	s_nop 1
	v_permlane32_swap_b32_e32 v33, v34
	v_add_f32_e32 v64, v33, v34
	v_fmac_f32_e32 v64, v127, v32
	v_cvt_pk_bf16_f32 v32, v142, v143
	v_cvt_pk_bf16_f32 v33, v160, v161
	v_cvt_pk_bf16_f32 v34, v164, v165
	v_cvt_pk_bf16_f32 v35, v166, v167
	v_cvt_pk_bf16_f32 v36, v168, v169
	v_cvt_pk_bf16_f32 v37, v170, v171
	v_cvt_pk_bf16_f32 v38, v172, v173
	v_cvt_pk_bf16_f32 v39, v174, v175
	v_cvt_pk_bf16_f32 v40, v40, v41
	v_cvt_pk_bf16_f32 v41, v42, v43
	v_cvt_pk_bf16_f32 v42, v149, v149
	v_cvt_pk_bf16_f32 v43, v149, v149
	ds_read_b64_tr_b16 v[44:45], v185 offset:0
	ds_read_b64_tr_b16 v[46:47], v185 offset:0x400
	ds_read_b64_tr_b16 v[48:49], v185 offset:0x800
	ds_read_b64_tr_b16 v[50:51], v185 offset:0xc00
	ds_read_b64_tr_b16 v[52:53], v185 offset:0x1000
	ds_read_b64_tr_b16 v[54:55], v185 offset:0x1400
	ds_read_b64_tr_b16 v[56:57], v185 offset:0x1800
	ds_read_b64_tr_b16 v[58:59], v185 offset:0x1c00
	s_waitcnt lgkmcnt(0)
	s_nop 0
	v_mfma_f32_32x32x16_bf16 v[16:31], v[44:47], v[32:35], v[16:31]
	s_mov_b32 s77, s76
	s_mov_b32 s78, s76
	s_mov_b32 s79, s76
	v_mov_b64_e32 v[44:45], s[76:77]
	v_mov_b64_e32 v[46:47], s[78:79]
	v_mfma_f32_32x32x16_bf16 v[16:31], v[48:51], v[36:39], v[16:31]
	ds_read_b64_tr_b16 v[48:49], v185 offset:0x200
	ds_read_b64_tr_b16 v[50:51], v185 offset:0x600
	v_mfma_f32_32x32x16_bf16 v[16:31], v[52:55], v[40:43], v[16:31]
	ds_read_b64_tr_b16 v[52:53], v185 offset:0xa00
	ds_read_b64_tr_b16 v[54:55], v185 offset:0xe00
	v_mfma_f32_32x32x16_bf16 v[16:31], v[56:59], v[44:47], v[16:31]
	ds_read_b64_tr_b16 v[56:57], v185 offset:0x1200
	ds_read_b64_tr_b16 v[58:59], v185 offset:0x1600
	ds_read_b64_tr_b16 v[60:61], v185 offset:0x1a00
	ds_read_b64_tr_b16 v[62:63], v185 offset:0x1e00
	s_waitcnt lgkmcnt(0)
	v_mfma_f32_32x32x16_bf16 v[0:15], v[48:51], v[32:35], v[0:15]
	v_mov_b32_e32 v127, v64
	v_mfma_f32_32x32x16_bf16 v[0:15], v[52:55], v[36:39], v[0:15]
	v_mfma_f32_32x32x16_bf16 v[0:15], v[56:59], v[40:43], v[0:15]
	v_mfma_f32_32x32x16_bf16 v[0:15], v[60:63], v[44:47], v[0:15]
	s_branch .LBB0_1084
